# adaLN modulation loop double-buffered (loads of the next 16 rows issued before computing the current 16)
# baseline (speedup 1.0000x reference)
; __device__ __forceinline__ float silu_f(float x) { return x * __builtin_amdgcn_rcpf(1.f + __builtin_amdgcn_exp2f(-x * 1.4426950408889634f)); }
; __device__ __forceinline__ void p0_prologue(const LArgs& a, LAS unsigned char* lds) {
;     ...
;             float a0 = 0.f, a1 = 0.f, a2 = 0.f;
; #pragma unroll 8
;             for (int k = 0; k < 256; ++k) { const float wv = w[(size_t)k * 12288]; a0 += pg8::silu_f(c0[k]) * wv; a1 += pg8::silu_f(c1[k]) * wv; a2 += pg8::silu_f(c2[k]) * wv; }
;             if (kc == 0) { const float bb = a.in(I_ADAB)[layer * 12288 + col]; a0 += bb; a1 += bb; a2 += bb; }
.Ladaln_pair:
	v_lshl_add_u64 v[8:9], v[30:31], 0, s[6:7]
	v_lshl_add_u64 v[44:45], v[32:33], 0, s[6:7]
	v_lshl_add_u64 v[10:11], v[8:9], 0, s[92:93]
	s_mov_b32 s2, 0xfffac000
	s_mov_b32 s3, -1
	v_lshl_add_u64 v[54:55], v[34:35], 0, s[2:3]
	global_load_dword v136, v[54:55], off
	s_mov_b64 s[2:3], 0xc000
	v_lshl_add_u64 v[56:57], v[54:55], 0, s[2:3]
	global_load_dword v137, v[56:57], off
	s_mov_b64 s[2:3], 0x18000
	v_lshl_add_u64 v[56:57], v[54:55], 0, s[2:3]
	global_load_dword v138, v[56:57], off
	s_mov_b64 s[2:3], 0x24000
	v_lshl_add_u64 v[56:57], v[54:55], 0, s[2:3]
	global_load_dword v139, v[56:57], off
	s_mov_b64 s[2:3], 0x30000
	v_lshl_add_u64 v[56:57], v[54:55], 0, s[2:3]
	global_load_dword v140, v[56:57], off
	s_mov_b64 s[2:3], 0x3c000
	v_lshl_add_u64 v[56:57], v[54:55], 0, s[2:3]
	global_load_dword v141, v[56:57], off
	s_mov_b64 s[2:3], 0x48000
	v_lshl_add_u64 v[56:57], v[54:55], 0, s[2:3]
	global_load_dword v142, v[56:57], off
	s_mov_b64 s[2:3], 0x54000
	v_lshl_add_u64 v[56:57], v[54:55], 0, s[2:3]
	global_load_dword v143, v[56:57], off
	s_mov_b64 s[2:3], 0x60000
	v_lshl_add_u64 v[56:57], v[54:55], 0, s[2:3]
	global_load_dword v144, v[56:57], off
	s_mov_b64 s[2:3], 0x6c000
	v_lshl_add_u64 v[56:57], v[54:55], 0, s[2:3]
	global_load_dword v145, v[56:57], off
	s_mov_b64 s[2:3], 0x78000
	v_lshl_add_u64 v[56:57], v[54:55], 0, s[2:3]
	global_load_dword v146, v[56:57], off
	s_mov_b64 s[2:3], 0x84000
	v_lshl_add_u64 v[56:57], v[54:55], 0, s[2:3]
	global_load_dword v147, v[56:57], off
	s_mov_b64 s[2:3], 0x90000
	v_lshl_add_u64 v[56:57], v[54:55], 0, s[2:3]
	global_load_dword v148, v[56:57], off
	s_mov_b64 s[2:3], 0x9c000
	v_lshl_add_u64 v[56:57], v[54:55], 0, s[2:3]
	global_load_dword v149, v[56:57], off
	s_mov_b64 s[2:3], 0xa8000
	v_lshl_add_u64 v[56:57], v[54:55], 0, s[2:3]
	global_load_dword v150, v[56:57], off
	s_mov_b64 s[2:3], 0xb4000
	v_lshl_add_u64 v[56:57], v[54:55], 0, s[2:3]
	global_load_dword v151, v[56:57], off
	global_load_dwordx4 v[152:155], v[8:9], off
	global_load_dwordx4 v[174:177], v[10:11], off
	global_load_dwordx4 v[202:205], v[44:45], off
	global_load_dwordx4 v[156:159], v[8:9], off offset:16
	global_load_dwordx4 v[178:181], v[10:11], off offset:16
	global_load_dwordx4 v[206:209], v[44:45], off offset:16
	global_load_dwordx4 v[160:163], v[8:9], off offset:32
	global_load_dwordx4 v[182:185], v[10:11], off offset:32
	global_load_dwordx4 v[210:213], v[44:45], off offset:32
	global_load_dwordx4 v[164:167], v[8:9], off offset:48
	global_load_dwordx4 v[186:189], v[10:11], off offset:48
	global_load_dwordx4 v[214:217], v[44:45], off offset:48
	s_mov_b64 s[2:3], 0xc0000
	v_lshl_add_u64 v[34:35], v[34:35], 0, s[2:3]
	s_add_u32 s6, s6, 64
	s_addc_u32 s7, s7, 0
	s_waitcnt vmcnt(28)
	v_mul_f32_e32 v4, 0xbfb8aa3b, v60
	v_mul_f32_e32 v5, 0xbfb8aa3b, v76
	v_mul_f32_e32 v6, 0xbfb8aa3b, v120
	v_exp_f32_e32 v4, v4
	v_exp_f32_e32 v5, v5
	v_exp_f32_e32 v6, v6
	v_add_f32_e32 v4, 1.0, v4
	v_add_f32_e32 v5, 1.0, v5
	v_add_f32_e32 v6, 1.0, v6
	v_rcp_f32_e32 v4, v4
	v_rcp_f32_e32 v5, v5
	v_rcp_f32_e32 v6, v6
	v_mul_f32_e32 v4, v60, v4
	v_mul_f32_e32 v5, v76, v5
	v_mul_f32_e32 v6, v120, v6
	v_fmac_f32_e32 v42, v100, v4
	v_fmac_f32_e32 v37, v100, v5
	v_fmac_f32_e32 v36, v100, v6
	v_mul_f32_e32 v4, 0xbfb8aa3b, v61
	v_mul_f32_e32 v5, 0xbfb8aa3b, v77
	v_mul_f32_e32 v6, 0xbfb8aa3b, v121
	v_exp_f32_e32 v4, v4
	v_exp_f32_e32 v5, v5
	v_exp_f32_e32 v6, v6
	v_add_f32_e32 v4, 1.0, v4
	v_add_f32_e32 v5, 1.0, v5
	v_add_f32_e32 v6, 1.0, v6
	v_rcp_f32_e32 v4, v4
	v_rcp_f32_e32 v5, v5
	v_rcp_f32_e32 v6, v6
	v_mul_f32_e32 v4, v61, v4
	v_mul_f32_e32 v5, v77, v5
	v_mul_f32_e32 v6, v121, v6
	v_fmac_f32_e32 v42, v101, v4
	v_fmac_f32_e32 v37, v101, v5
	v_fmac_f32_e32 v36, v101, v6
	v_mul_f32_e32 v4, 0xbfb8aa3b, v62
	v_mul_f32_e32 v5, 0xbfb8aa3b, v78
	v_mul_f32_e32 v6, 0xbfb8aa3b, v122
	v_exp_f32_e32 v4, v4
	v_exp_f32_e32 v5, v5
	v_exp_f32_e32 v6, v6
	v_add_f32_e32 v4, 1.0, v4
	v_add_f32_e32 v5, 1.0, v5
	v_add_f32_e32 v6, 1.0, v6
	v_rcp_f32_e32 v4, v4
	v_rcp_f32_e32 v5, v5
	v_rcp_f32_e32 v6, v6
	v_mul_f32_e32 v4, v62, v4
	v_mul_f32_e32 v5, v78, v5
	v_mul_f32_e32 v6, v122, v6
	v_fmac_f32_e32 v42, v102, v4
	v_fmac_f32_e32 v37, v102, v5
	v_fmac_f32_e32 v36, v102, v6
	v_mul_f32_e32 v4, 0xbfb8aa3b, v63
	v_mul_f32_e32 v5, 0xbfb8aa3b, v79
	v_mul_f32_e32 v6, 0xbfb8aa3b, v123
	v_exp_f32_e32 v4, v4
	v_exp_f32_e32 v5, v5
	v_exp_f32_e32 v6, v6
	v_add_f32_e32 v4, 1.0, v4
	v_add_f32_e32 v5, 1.0, v5
	v_add_f32_e32 v6, 1.0, v6
	v_rcp_f32_e32 v4, v4
	v_rcp_f32_e32 v5, v5
	v_rcp_f32_e32 v6, v6
	v_mul_f32_e32 v4, v63, v4
	v_mul_f32_e32 v5, v79, v5
	v_mul_f32_e32 v6, v123, v6
	v_fmac_f32_e32 v42, v103, v4
	v_fmac_f32_e32 v37, v103, v5
	v_fmac_f32_e32 v36, v103, v6
	v_mul_f32_e32 v4, 0xbfb8aa3b, v64
	v_mul_f32_e32 v5, 0xbfb8aa3b, v80
	v_mul_f32_e32 v6, 0xbfb8aa3b, v124
	v_exp_f32_e32 v4, v4
	v_exp_f32_e32 v5, v5
	v_exp_f32_e32 v6, v6
	v_add_f32_e32 v4, 1.0, v4
	v_add_f32_e32 v5, 1.0, v5
	v_add_f32_e32 v6, 1.0, v6
	v_rcp_f32_e32 v4, v4
	v_rcp_f32_e32 v5, v5
	v_rcp_f32_e32 v6, v6
	v_mul_f32_e32 v4, v64, v4
	v_mul_f32_e32 v5, v80, v5
	v_mul_f32_e32 v6, v124, v6
	v_fmac_f32_e32 v42, v104, v4
	v_fmac_f32_e32 v37, v104, v5
	v_fmac_f32_e32 v36, v104, v6
	v_mul_f32_e32 v4, 0xbfb8aa3b, v65
	v_mul_f32_e32 v5, 0xbfb8aa3b, v81
	v_mul_f32_e32 v6, 0xbfb8aa3b, v125
	v_exp_f32_e32 v4, v4
	v_exp_f32_e32 v5, v5
	v_exp_f32_e32 v6, v6
	v_add_f32_e32 v4, 1.0, v4
	v_add_f32_e32 v5, 1.0, v5
	v_add_f32_e32 v6, 1.0, v6
	v_rcp_f32_e32 v4, v4
	v_rcp_f32_e32 v5, v5
	v_rcp_f32_e32 v6, v6
	v_mul_f32_e32 v4, v65, v4
	v_mul_f32_e32 v5, v81, v5
	v_mul_f32_e32 v6, v125, v6
	v_fmac_f32_e32 v42, v105, v4
; __device__ __forceinline__ float silu_f(float x) { return x * __builtin_amdgcn_rcpf(1.f + __builtin_amdgcn_exp2f(-x * 1.4426950408889634f)); }
; __device__ __forceinline__ void p0_prologue(const LArgs& a, LAS unsigned char* lds) {
;     ...
; #pragma unroll 8
;             for (int k = 0; k < 256; ++k) { const float wv = w[(size_t)k * 12288]; a0 += pg8::silu_f(c0[k]) * wv; a1 += pg8::silu_f(c1[k]) * wv; a2 += pg8::silu_f(c2[k]) * wv; }
	v_fmac_f32_e32 v37, v105, v5
	v_fmac_f32_e32 v36, v105, v6
	v_mul_f32_e32 v4, 0xbfb8aa3b, v66
	v_mul_f32_e32 v5, 0xbfb8aa3b, v82
	v_mul_f32_e32 v6, 0xbfb8aa3b, v126
	v_exp_f32_e32 v4, v4
	v_exp_f32_e32 v5, v5
	v_exp_f32_e32 v6, v6
	v_add_f32_e32 v4, 1.0, v4
	v_add_f32_e32 v5, 1.0, v5
	v_add_f32_e32 v6, 1.0, v6
	v_rcp_f32_e32 v4, v4
	v_rcp_f32_e32 v5, v5
	v_rcp_f32_e32 v6, v6
	v_mul_f32_e32 v4, v66, v4
	v_mul_f32_e32 v5, v82, v5
	v_mul_f32_e32 v6, v126, v6
	v_fmac_f32_e32 v42, v106, v4
	v_fmac_f32_e32 v37, v106, v5
	v_fmac_f32_e32 v36, v106, v6
	v_mul_f32_e32 v4, 0xbfb8aa3b, v67
	v_mul_f32_e32 v5, 0xbfb8aa3b, v83
	v_mul_f32_e32 v6, 0xbfb8aa3b, v127
	v_exp_f32_e32 v4, v4
	v_exp_f32_e32 v5, v5
	v_exp_f32_e32 v6, v6
	v_add_f32_e32 v4, 1.0, v4
	v_add_f32_e32 v5, 1.0, v5
	v_add_f32_e32 v6, 1.0, v6
	v_rcp_f32_e32 v4, v4
	v_rcp_f32_e32 v5, v5
	v_rcp_f32_e32 v6, v6
	v_mul_f32_e32 v4, v67, v4
	v_mul_f32_e32 v5, v83, v5
	v_mul_f32_e32 v6, v127, v6
	v_fmac_f32_e32 v42, v107, v4
	v_fmac_f32_e32 v37, v107, v5
	v_fmac_f32_e32 v36, v107, v6
	v_mul_f32_e32 v4, 0xbfb8aa3b, v68
	v_mul_f32_e32 v5, 0xbfb8aa3b, v84
	v_mul_f32_e32 v6, 0xbfb8aa3b, v128
	v_exp_f32_e32 v4, v4
	v_exp_f32_e32 v5, v5
	v_exp_f32_e32 v6, v6
	v_add_f32_e32 v4, 1.0, v4
	v_add_f32_e32 v5, 1.0, v5
	v_add_f32_e32 v6, 1.0, v6
	v_rcp_f32_e32 v4, v4
	v_rcp_f32_e32 v5, v5
	v_rcp_f32_e32 v6, v6
	v_mul_f32_e32 v4, v68, v4
	v_mul_f32_e32 v5, v84, v5
	v_mul_f32_e32 v6, v128, v6
	v_fmac_f32_e32 v42, v108, v4
	v_fmac_f32_e32 v37, v108, v5
	v_fmac_f32_e32 v36, v108, v6
	v_mul_f32_e32 v4, 0xbfb8aa3b, v69
	v_mul_f32_e32 v5, 0xbfb8aa3b, v85
	v_mul_f32_e32 v6, 0xbfb8aa3b, v129
	v_exp_f32_e32 v4, v4
	v_exp_f32_e32 v5, v5
	v_exp_f32_e32 v6, v6
	v_add_f32_e32 v4, 1.0, v4
	v_add_f32_e32 v5, 1.0, v5
	v_add_f32_e32 v6, 1.0, v6
	v_rcp_f32_e32 v4, v4
	v_rcp_f32_e32 v5, v5
	v_rcp_f32_e32 v6, v6
	v_mul_f32_e32 v4, v69, v4
	v_mul_f32_e32 v5, v85, v5
	v_mul_f32_e32 v6, v129, v6
	v_fmac_f32_e32 v42, v109, v4
	v_fmac_f32_e32 v37, v109, v5
	v_fmac_f32_e32 v36, v109, v6
	v_mul_f32_e32 v4, 0xbfb8aa3b, v70
	v_mul_f32_e32 v5, 0xbfb8aa3b, v86
	v_mul_f32_e32 v6, 0xbfb8aa3b, v130
	v_exp_f32_e32 v4, v4
	v_exp_f32_e32 v5, v5
	v_exp_f32_e32 v6, v6
	v_add_f32_e32 v4, 1.0, v4
	v_add_f32_e32 v5, 1.0, v5
	v_add_f32_e32 v6, 1.0, v6
	v_rcp_f32_e32 v4, v4
	v_rcp_f32_e32 v5, v5
	v_rcp_f32_e32 v6, v6
	v_mul_f32_e32 v4, v70, v4
	v_mul_f32_e32 v5, v86, v5
	v_mul_f32_e32 v6, v130, v6
	v_fmac_f32_e32 v42, v110, v4
	v_fmac_f32_e32 v37, v110, v5
	v_fmac_f32_e32 v36, v110, v6
	v_mul_f32_e32 v4, 0xbfb8aa3b, v71
	v_mul_f32_e32 v5, 0xbfb8aa3b, v87
	v_mul_f32_e32 v6, 0xbfb8aa3b, v131
	v_exp_f32_e32 v4, v4
	v_exp_f32_e32 v5, v5
	v_exp_f32_e32 v6, v6
	v_add_f32_e32 v4, 1.0, v4
	v_add_f32_e32 v5, 1.0, v5
	v_add_f32_e32 v6, 1.0, v6
	v_rcp_f32_e32 v4, v4
	v_rcp_f32_e32 v5, v5
	v_rcp_f32_e32 v6, v6
	v_mul_f32_e32 v4, v71, v4
	v_mul_f32_e32 v5, v87, v5
	v_mul_f32_e32 v6, v131, v6
	v_fmac_f32_e32 v42, v111, v4
	v_fmac_f32_e32 v37, v111, v5
	v_fmac_f32_e32 v36, v111, v6
	v_mul_f32_e32 v4, 0xbfb8aa3b, v72
	v_mul_f32_e32 v5, 0xbfb8aa3b, v88
	v_mul_f32_e32 v6, 0xbfb8aa3b, v132
	v_exp_f32_e32 v4, v4
	v_exp_f32_e32 v5, v5
	v_exp_f32_e32 v6, v6
	v_add_f32_e32 v4, 1.0, v4
	v_add_f32_e32 v5, 1.0, v5
	v_add_f32_e32 v6, 1.0, v6
	v_rcp_f32_e32 v4, v4
	v_rcp_f32_e32 v5, v5
	v_rcp_f32_e32 v6, v6
	v_mul_f32_e32 v4, v72, v4
	v_mul_f32_e32 v5, v88, v5
	v_mul_f32_e32 v6, v132, v6
	v_fmac_f32_e32 v42, v112, v4
	v_fmac_f32_e32 v37, v112, v5
	v_fmac_f32_e32 v36, v112, v6
	v_mul_f32_e32 v4, 0xbfb8aa3b, v73
	v_mul_f32_e32 v5, 0xbfb8aa3b, v89
	v_mul_f32_e32 v6, 0xbfb8aa3b, v133
	v_exp_f32_e32 v4, v4
	v_exp_f32_e32 v5, v5
	v_exp_f32_e32 v6, v6
	v_add_f32_e32 v4, 1.0, v4
	v_add_f32_e32 v5, 1.0, v5
	v_add_f32_e32 v6, 1.0, v6
	v_rcp_f32_e32 v4, v4
	v_rcp_f32_e32 v5, v5
	v_rcp_f32_e32 v6, v6
	v_mul_f32_e32 v4, v73, v4
	v_mul_f32_e32 v5, v89, v5
	v_mul_f32_e32 v6, v133, v6
	v_fmac_f32_e32 v42, v113, v4
	v_fmac_f32_e32 v37, v113, v5
	v_fmac_f32_e32 v36, v113, v6
	v_mul_f32_e32 v4, 0xbfb8aa3b, v74
	v_mul_f32_e32 v5, 0xbfb8aa3b, v90
	v_mul_f32_e32 v6, 0xbfb8aa3b, v134
	v_exp_f32_e32 v4, v4
	v_exp_f32_e32 v5, v5
	v_exp_f32_e32 v6, v6
	v_add_f32_e32 v4, 1.0, v4
	v_add_f32_e32 v5, 1.0, v5
	v_add_f32_e32 v6, 1.0, v6
	v_rcp_f32_e32 v4, v4
	v_rcp_f32_e32 v5, v5
	v_rcp_f32_e32 v6, v6
	v_mul_f32_e32 v4, v74, v4
	v_mul_f32_e32 v5, v90, v5
	v_mul_f32_e32 v6, v134, v6
	v_fmac_f32_e32 v42, v114, v4
	v_fmac_f32_e32 v37, v114, v5
	v_fmac_f32_e32 v36, v114, v6
	v_mul_f32_e32 v4, 0xbfb8aa3b, v75
	v_mul_f32_e32 v5, 0xbfb8aa3b, v91
	v_mul_f32_e32 v6, 0xbfb8aa3b, v135
	v_exp_f32_e32 v4, v4
	v_exp_f32_e32 v5, v5
	v_exp_f32_e32 v6, v6
	v_add_f32_e32 v4, 1.0, v4
	v_add_f32_e32 v5, 1.0, v5
	v_add_f32_e32 v6, 1.0, v6
	v_rcp_f32_e32 v4, v4
	v_rcp_f32_e32 v5, v5
	v_rcp_f32_e32 v6, v6
	v_mul_f32_e32 v4, v75, v4
	v_mul_f32_e32 v5, v91, v5
	v_mul_f32_e32 v6, v135, v6
	v_fmac_f32_e32 v42, v115, v4
	v_fmac_f32_e32 v37, v115, v5
	v_fmac_f32_e32 v36, v115, v6
	s_cmpk_eq_i32 s6, 0x400
	s_cbranch_scc1 .Ladaln_lastB
; __device__ __forceinline__ float silu_f(float x) { return x * __builtin_amdgcn_rcpf(1.f + __builtin_amdgcn_exp2f(-x * 1.4426950408889634f)); }
; __device__ __forceinline__ void p0_prologue(const LArgs& a, LAS unsigned char* lds) {
;     ...
; #pragma unroll 8
;             for (int k = 0; k < 256; ++k) { const float wv = w[(size_t)k * 12288]; a0 += pg8::silu_f(c0[k]) * wv; a1 += pg8::silu_f(c1[k]) * wv; a2 += pg8::silu_f(c2[k]) * wv; }
	v_lshl_add_u64 v[8:9], v[30:31], 0, s[6:7]
	v_lshl_add_u64 v[44:45], v[32:33], 0, s[6:7]
	v_lshl_add_u64 v[10:11], v[8:9], 0, s[92:93]
	s_mov_b32 s2, 0xfffac000
	s_mov_b32 s3, -1
	v_lshl_add_u64 v[54:55], v[34:35], 0, s[2:3]
	global_load_dword v100, v[54:55], off
	s_mov_b64 s[2:3], 0xc000
	v_lshl_add_u64 v[56:57], v[54:55], 0, s[2:3]
	global_load_dword v101, v[56:57], off
	s_mov_b64 s[2:3], 0x18000
	v_lshl_add_u64 v[56:57], v[54:55], 0, s[2:3]
	global_load_dword v102, v[56:57], off
	s_mov_b64 s[2:3], 0x24000
	v_lshl_add_u64 v[56:57], v[54:55], 0, s[2:3]
	global_load_dword v103, v[56:57], off
	s_mov_b64 s[2:3], 0x30000
	v_lshl_add_u64 v[56:57], v[54:55], 0, s[2:3]
	global_load_dword v104, v[56:57], off
	s_mov_b64 s[2:3], 0x3c000
	v_lshl_add_u64 v[56:57], v[54:55], 0, s[2:3]
	global_load_dword v105, v[56:57], off
	s_mov_b64 s[2:3], 0x48000
	v_lshl_add_u64 v[56:57], v[54:55], 0, s[2:3]
	global_load_dword v106, v[56:57], off
	s_mov_b64 s[2:3], 0x54000
	v_lshl_add_u64 v[56:57], v[54:55], 0, s[2:3]
	global_load_dword v107, v[56:57], off
	s_mov_b64 s[2:3], 0x60000
	v_lshl_add_u64 v[56:57], v[54:55], 0, s[2:3]
	global_load_dword v108, v[56:57], off
	s_mov_b64 s[2:3], 0x6c000
	v_lshl_add_u64 v[56:57], v[54:55], 0, s[2:3]
	global_load_dword v109, v[56:57], off
	s_mov_b64 s[2:3], 0x78000
	v_lshl_add_u64 v[56:57], v[54:55], 0, s[2:3]
	global_load_dword v110, v[56:57], off
	s_mov_b64 s[2:3], 0x84000
	v_lshl_add_u64 v[56:57], v[54:55], 0, s[2:3]
	global_load_dword v111, v[56:57], off
	s_mov_b64 s[2:3], 0x90000
	v_lshl_add_u64 v[56:57], v[54:55], 0, s[2:3]
	global_load_dword v112, v[56:57], off
	s_mov_b64 s[2:3], 0x9c000
	v_lshl_add_u64 v[56:57], v[54:55], 0, s[2:3]
	global_load_dword v113, v[56:57], off
	s_mov_b64 s[2:3], 0xa8000
	v_lshl_add_u64 v[56:57], v[54:55], 0, s[2:3]
	global_load_dword v114, v[56:57], off
	s_mov_b64 s[2:3], 0xb4000
	v_lshl_add_u64 v[56:57], v[54:55], 0, s[2:3]
	global_load_dword v115, v[56:57], off
	global_load_dwordx4 v[60:63], v[8:9], off
	global_load_dwordx4 v[76:79], v[10:11], off
	global_load_dwordx4 v[120:123], v[44:45], off
	global_load_dwordx4 v[64:67], v[8:9], off offset:16
	global_load_dwordx4 v[80:83], v[10:11], off offset:16
	global_load_dwordx4 v[124:127], v[44:45], off offset:16
	global_load_dwordx4 v[68:71], v[8:9], off offset:32
	global_load_dwordx4 v[84:87], v[10:11], off offset:32
	global_load_dwordx4 v[128:131], v[44:45], off offset:32
	global_load_dwordx4 v[72:75], v[8:9], off offset:48
	global_load_dwordx4 v[88:91], v[10:11], off offset:48
	global_load_dwordx4 v[132:135], v[44:45], off offset:48
	s_mov_b64 s[2:3], 0xc0000
	v_lshl_add_u64 v[34:35], v[34:35], 0, s[2:3]
	s_add_u32 s6, s6, 64
	s_addc_u32 s7, s7, 0
	s_waitcnt vmcnt(28)
	v_mul_f32_e32 v4, 0xbfb8aa3b, v152
	v_mul_f32_e32 v5, 0xbfb8aa3b, v174
	v_mul_f32_e32 v6, 0xbfb8aa3b, v202
	v_exp_f32_e32 v4, v4
	v_exp_f32_e32 v5, v5
	v_exp_f32_e32 v6, v6
	v_add_f32_e32 v4, 1.0, v4
	v_add_f32_e32 v5, 1.0, v5
	v_add_f32_e32 v6, 1.0, v6
	v_rcp_f32_e32 v4, v4
	v_rcp_f32_e32 v5, v5
	v_rcp_f32_e32 v6, v6
	v_mul_f32_e32 v4, v152, v4
	v_mul_f32_e32 v5, v174, v5
	v_mul_f32_e32 v6, v202, v6
	v_fmac_f32_e32 v42, v136, v4
	v_fmac_f32_e32 v37, v136, v5
	v_fmac_f32_e32 v36, v136, v6
	v_mul_f32_e32 v4, 0xbfb8aa3b, v153
	v_mul_f32_e32 v5, 0xbfb8aa3b, v175
	v_mul_f32_e32 v6, 0xbfb8aa3b, v203
	v_exp_f32_e32 v4, v4
	v_exp_f32_e32 v5, v5
	v_exp_f32_e32 v6, v6
	v_add_f32_e32 v4, 1.0, v4
	v_add_f32_e32 v5, 1.0, v5
	v_add_f32_e32 v6, 1.0, v6
	v_rcp_f32_e32 v4, v4
	v_rcp_f32_e32 v5, v5
	v_rcp_f32_e32 v6, v6
	v_mul_f32_e32 v4, v153, v4
	v_mul_f32_e32 v5, v175, v5
	v_mul_f32_e32 v6, v203, v6
	v_fmac_f32_e32 v42, v137, v4
	v_fmac_f32_e32 v37, v137, v5
	v_fmac_f32_e32 v36, v137, v6
	v_mul_f32_e32 v4, 0xbfb8aa3b, v154
	v_mul_f32_e32 v5, 0xbfb8aa3b, v176
	v_mul_f32_e32 v6, 0xbfb8aa3b, v204
	v_exp_f32_e32 v4, v4
	v_exp_f32_e32 v5, v5
	v_exp_f32_e32 v6, v6
	v_add_f32_e32 v4, 1.0, v4
	v_add_f32_e32 v5, 1.0, v5
	v_add_f32_e32 v6, 1.0, v6
	v_rcp_f32_e32 v4, v4
	v_rcp_f32_e32 v5, v5
	v_rcp_f32_e32 v6, v6
	v_mul_f32_e32 v4, v154, v4
	v_mul_f32_e32 v5, v176, v5
	v_mul_f32_e32 v6, v204, v6
	v_fmac_f32_e32 v42, v138, v4
	v_fmac_f32_e32 v37, v138, v5
	v_fmac_f32_e32 v36, v138, v6
	v_mul_f32_e32 v4, 0xbfb8aa3b, v155
	v_mul_f32_e32 v5, 0xbfb8aa3b, v177
	v_mul_f32_e32 v6, 0xbfb8aa3b, v205
	v_exp_f32_e32 v4, v4
	v_exp_f32_e32 v5, v5
	v_exp_f32_e32 v6, v6
	v_add_f32_e32 v4, 1.0, v4
	v_add_f32_e32 v5, 1.0, v5
	v_add_f32_e32 v6, 1.0, v6
	v_rcp_f32_e32 v4, v4
	v_rcp_f32_e32 v5, v5
	v_rcp_f32_e32 v6, v6
	v_mul_f32_e32 v4, v155, v4
	v_mul_f32_e32 v5, v177, v5
	v_mul_f32_e32 v6, v205, v6
	v_fmac_f32_e32 v42, v139, v4
	v_fmac_f32_e32 v37, v139, v5
	v_fmac_f32_e32 v36, v139, v6
	v_mul_f32_e32 v4, 0xbfb8aa3b, v156
	v_mul_f32_e32 v5, 0xbfb8aa3b, v178
	v_mul_f32_e32 v6, 0xbfb8aa3b, v206
	v_exp_f32_e32 v4, v4
	v_exp_f32_e32 v5, v5
	v_exp_f32_e32 v6, v6
	v_add_f32_e32 v4, 1.0, v4
	v_add_f32_e32 v5, 1.0, v5
	v_add_f32_e32 v6, 1.0, v6
	v_rcp_f32_e32 v4, v4
	v_rcp_f32_e32 v5, v5
	v_rcp_f32_e32 v6, v6
	v_mul_f32_e32 v4, v156, v4
	v_mul_f32_e32 v5, v178, v5
	v_mul_f32_e32 v6, v206, v6
	v_fmac_f32_e32 v42, v140, v4
	v_fmac_f32_e32 v37, v140, v5
	v_fmac_f32_e32 v36, v140, v6
	v_mul_f32_e32 v4, 0xbfb8aa3b, v157
	v_mul_f32_e32 v5, 0xbfb8aa3b, v179
	v_mul_f32_e32 v6, 0xbfb8aa3b, v207
	v_exp_f32_e32 v4, v4
	v_exp_f32_e32 v5, v5
	v_exp_f32_e32 v6, v6
	v_add_f32_e32 v4, 1.0, v4
	v_add_f32_e32 v5, 1.0, v5
	v_add_f32_e32 v6, 1.0, v6
	v_rcp_f32_e32 v4, v4
	v_rcp_f32_e32 v5, v5
	v_rcp_f32_e32 v6, v6
	v_mul_f32_e32 v4, v157, v4
	v_mul_f32_e32 v5, v179, v5
	v_mul_f32_e32 v6, v207, v6
	v_fmac_f32_e32 v42, v141, v4
	v_fmac_f32_e32 v37, v141, v5
; __device__ __forceinline__ float silu_f(float x) { return x * __builtin_amdgcn_rcpf(1.f + __builtin_amdgcn_exp2f(-x * 1.4426950408889634f)); }
; __device__ __forceinline__ void p0_prologue(const LArgs& a, LAS unsigned char* lds) {
;     ...
; #pragma unroll 8
;             for (int k = 0; k < 256; ++k) { const float wv = w[(size_t)k * 12288]; a0 += pg8::silu_f(c0[k]) * wv; a1 += pg8::silu_f(c1[k]) * wv; a2 += pg8::silu_f(c2[k]) * wv; }
	v_fmac_f32_e32 v36, v141, v6
	v_mul_f32_e32 v4, 0xbfb8aa3b, v158
	v_mul_f32_e32 v5, 0xbfb8aa3b, v180
	v_mul_f32_e32 v6, 0xbfb8aa3b, v208
	v_exp_f32_e32 v4, v4
	v_exp_f32_e32 v5, v5
	v_exp_f32_e32 v6, v6
	v_add_f32_e32 v4, 1.0, v4
	v_add_f32_e32 v5, 1.0, v5
	v_add_f32_e32 v6, 1.0, v6
	v_rcp_f32_e32 v4, v4
	v_rcp_f32_e32 v5, v5
	v_rcp_f32_e32 v6, v6
	v_mul_f32_e32 v4, v158, v4
	v_mul_f32_e32 v5, v180, v5
	v_mul_f32_e32 v6, v208, v6
	v_fmac_f32_e32 v42, v142, v4
	v_fmac_f32_e32 v37, v142, v5
	v_fmac_f32_e32 v36, v142, v6
	v_mul_f32_e32 v4, 0xbfb8aa3b, v159
	v_mul_f32_e32 v5, 0xbfb8aa3b, v181
	v_mul_f32_e32 v6, 0xbfb8aa3b, v209
	v_exp_f32_e32 v4, v4
	v_exp_f32_e32 v5, v5
	v_exp_f32_e32 v6, v6
	v_add_f32_e32 v4, 1.0, v4
	v_add_f32_e32 v5, 1.0, v5
	v_add_f32_e32 v6, 1.0, v6
	v_rcp_f32_e32 v4, v4
	v_rcp_f32_e32 v5, v5
	v_rcp_f32_e32 v6, v6
	v_mul_f32_e32 v4, v159, v4
	v_mul_f32_e32 v5, v181, v5
	v_mul_f32_e32 v6, v209, v6
	v_fmac_f32_e32 v42, v143, v4
	v_fmac_f32_e32 v37, v143, v5
	v_fmac_f32_e32 v36, v143, v6
	v_mul_f32_e32 v4, 0xbfb8aa3b, v160
	v_mul_f32_e32 v5, 0xbfb8aa3b, v182
	v_mul_f32_e32 v6, 0xbfb8aa3b, v210
	v_exp_f32_e32 v4, v4
	v_exp_f32_e32 v5, v5
	v_exp_f32_e32 v6, v6
	v_add_f32_e32 v4, 1.0, v4
	v_add_f32_e32 v5, 1.0, v5
	v_add_f32_e32 v6, 1.0, v6
	v_rcp_f32_e32 v4, v4
	v_rcp_f32_e32 v5, v5
	v_rcp_f32_e32 v6, v6
	v_mul_f32_e32 v4, v160, v4
	v_mul_f32_e32 v5, v182, v5
	v_mul_f32_e32 v6, v210, v6
	v_fmac_f32_e32 v42, v144, v4
	v_fmac_f32_e32 v37, v144, v5
	v_fmac_f32_e32 v36, v144, v6
	v_mul_f32_e32 v4, 0xbfb8aa3b, v161
	v_mul_f32_e32 v5, 0xbfb8aa3b, v183
	v_mul_f32_e32 v6, 0xbfb8aa3b, v211
	v_exp_f32_e32 v4, v4
	v_exp_f32_e32 v5, v5
	v_exp_f32_e32 v6, v6
	v_add_f32_e32 v4, 1.0, v4
	v_add_f32_e32 v5, 1.0, v5
	v_add_f32_e32 v6, 1.0, v6
	v_rcp_f32_e32 v4, v4
	v_rcp_f32_e32 v5, v5
	v_rcp_f32_e32 v6, v6
	v_mul_f32_e32 v4, v161, v4
	v_mul_f32_e32 v5, v183, v5
	v_mul_f32_e32 v6, v211, v6
	v_fmac_f32_e32 v42, v145, v4
	v_fmac_f32_e32 v37, v145, v5
	v_fmac_f32_e32 v36, v145, v6
	v_mul_f32_e32 v4, 0xbfb8aa3b, v162
	v_mul_f32_e32 v5, 0xbfb8aa3b, v184
	v_mul_f32_e32 v6, 0xbfb8aa3b, v212
	v_exp_f32_e32 v4, v4
	v_exp_f32_e32 v5, v5
	v_exp_f32_e32 v6, v6
	v_add_f32_e32 v4, 1.0, v4
	v_add_f32_e32 v5, 1.0, v5
	v_add_f32_e32 v6, 1.0, v6
	v_rcp_f32_e32 v4, v4
	v_rcp_f32_e32 v5, v5
	v_rcp_f32_e32 v6, v6
	v_mul_f32_e32 v4, v162, v4
	v_mul_f32_e32 v5, v184, v5
	v_mul_f32_e32 v6, v212, v6
	v_fmac_f32_e32 v42, v146, v4
	v_fmac_f32_e32 v37, v146, v5
	v_fmac_f32_e32 v36, v146, v6
	v_mul_f32_e32 v4, 0xbfb8aa3b, v163
	v_mul_f32_e32 v5, 0xbfb8aa3b, v185
	v_mul_f32_e32 v6, 0xbfb8aa3b, v213
	v_exp_f32_e32 v4, v4
	v_exp_f32_e32 v5, v5
	v_exp_f32_e32 v6, v6
	v_add_f32_e32 v4, 1.0, v4
	v_add_f32_e32 v5, 1.0, v5
	v_add_f32_e32 v6, 1.0, v6
	v_rcp_f32_e32 v4, v4
	v_rcp_f32_e32 v5, v5
	v_rcp_f32_e32 v6, v6
	v_mul_f32_e32 v4, v163, v4
	v_mul_f32_e32 v5, v185, v5
	v_mul_f32_e32 v6, v213, v6
	v_fmac_f32_e32 v42, v147, v4
	v_fmac_f32_e32 v37, v147, v5
	v_fmac_f32_e32 v36, v147, v6
	v_mul_f32_e32 v4, 0xbfb8aa3b, v164
	v_mul_f32_e32 v5, 0xbfb8aa3b, v186
	v_mul_f32_e32 v6, 0xbfb8aa3b, v214
	v_exp_f32_e32 v4, v4
	v_exp_f32_e32 v5, v5
	v_exp_f32_e32 v6, v6
	v_add_f32_e32 v4, 1.0, v4
	v_add_f32_e32 v5, 1.0, v5
	v_add_f32_e32 v6, 1.0, v6
	v_rcp_f32_e32 v4, v4
	v_rcp_f32_e32 v5, v5
	v_rcp_f32_e32 v6, v6
	v_mul_f32_e32 v4, v164, v4
	v_mul_f32_e32 v5, v186, v5
	v_mul_f32_e32 v6, v214, v6
	v_fmac_f32_e32 v42, v148, v4
	v_fmac_f32_e32 v37, v148, v5
	v_fmac_f32_e32 v36, v148, v6
	v_mul_f32_e32 v4, 0xbfb8aa3b, v165
	v_mul_f32_e32 v5, 0xbfb8aa3b, v187
	v_mul_f32_e32 v6, 0xbfb8aa3b, v215
	v_exp_f32_e32 v4, v4
	v_exp_f32_e32 v5, v5
	v_exp_f32_e32 v6, v6
	v_add_f32_e32 v4, 1.0, v4
	v_add_f32_e32 v5, 1.0, v5
	v_add_f32_e32 v6, 1.0, v6
	v_rcp_f32_e32 v4, v4
	v_rcp_f32_e32 v5, v5
	v_rcp_f32_e32 v6, v6
	v_mul_f32_e32 v4, v165, v4
	v_mul_f32_e32 v5, v187, v5
	v_mul_f32_e32 v6, v215, v6
	v_fmac_f32_e32 v42, v149, v4
	v_fmac_f32_e32 v37, v149, v5
	v_fmac_f32_e32 v36, v149, v6
	v_mul_f32_e32 v4, 0xbfb8aa3b, v166
	v_mul_f32_e32 v5, 0xbfb8aa3b, v188
	v_mul_f32_e32 v6, 0xbfb8aa3b, v216
	v_exp_f32_e32 v4, v4
	v_exp_f32_e32 v5, v5
	v_exp_f32_e32 v6, v6
	v_add_f32_e32 v4, 1.0, v4
	v_add_f32_e32 v5, 1.0, v5
	v_add_f32_e32 v6, 1.0, v6
	v_rcp_f32_e32 v4, v4
	v_rcp_f32_e32 v5, v5
	v_rcp_f32_e32 v6, v6
	v_mul_f32_e32 v4, v166, v4
	v_mul_f32_e32 v5, v188, v5
	v_mul_f32_e32 v6, v216, v6
	v_fmac_f32_e32 v42, v150, v4
	v_fmac_f32_e32 v37, v150, v5
	v_fmac_f32_e32 v36, v150, v6
	v_mul_f32_e32 v4, 0xbfb8aa3b, v167
	v_mul_f32_e32 v5, 0xbfb8aa3b, v189
	v_mul_f32_e32 v6, 0xbfb8aa3b, v217
	v_exp_f32_e32 v4, v4
	v_exp_f32_e32 v5, v5
	v_exp_f32_e32 v6, v6
	v_add_f32_e32 v4, 1.0, v4
	v_add_f32_e32 v5, 1.0, v5
	v_add_f32_e32 v6, 1.0, v6
	v_rcp_f32_e32 v4, v4
	v_rcp_f32_e32 v5, v5
	v_rcp_f32_e32 v6, v6
	v_mul_f32_e32 v4, v167, v4
	v_mul_f32_e32 v5, v189, v5
	v_mul_f32_e32 v6, v217, v6
	v_fmac_f32_e32 v42, v151, v4
	v_fmac_f32_e32 v37, v151, v5
	v_fmac_f32_e32 v36, v151, v6
	s_branch .Ladaln_pair
; __device__ __forceinline__ float silu_f(float x) { return x * __builtin_amdgcn_rcpf(1.f + __builtin_amdgcn_exp2f(-x * 1.4426950408889634f)); }
; __device__ __forceinline__ void p0_prologue(const LArgs& a, LAS unsigned char* lds) {
;     ...
; #pragma unroll 8
;             for (int k = 0; k < 256; ++k) { const float wv = w[(size_t)k * 12288]; a0 += pg8::silu_f(c0[k]) * wv; a1 += pg8::silu_f(c1[k]) * wv; a2 += pg8::silu_f(c2[k]) * wv; }
.Ladaln_lastB:
	s_waitcnt vmcnt(0)
	v_mul_f32_e32 v4, 0xbfb8aa3b, v152
	v_mul_f32_e32 v5, 0xbfb8aa3b, v174
	v_mul_f32_e32 v6, 0xbfb8aa3b, v202
	v_exp_f32_e32 v4, v4
	v_exp_f32_e32 v5, v5
	v_exp_f32_e32 v6, v6
	v_add_f32_e32 v4, 1.0, v4
	v_add_f32_e32 v5, 1.0, v5
	v_add_f32_e32 v6, 1.0, v6
	v_rcp_f32_e32 v4, v4
	v_rcp_f32_e32 v5, v5
	v_rcp_f32_e32 v6, v6
	v_mul_f32_e32 v4, v152, v4
	v_mul_f32_e32 v5, v174, v5
	v_mul_f32_e32 v6, v202, v6
	v_fmac_f32_e32 v42, v136, v4
	v_fmac_f32_e32 v37, v136, v5
	v_fmac_f32_e32 v36, v136, v6
	v_mul_f32_e32 v4, 0xbfb8aa3b, v153
	v_mul_f32_e32 v5, 0xbfb8aa3b, v175
	v_mul_f32_e32 v6, 0xbfb8aa3b, v203
	v_exp_f32_e32 v4, v4
	v_exp_f32_e32 v5, v5
	v_exp_f32_e32 v6, v6
	v_add_f32_e32 v4, 1.0, v4
	v_add_f32_e32 v5, 1.0, v5
	v_add_f32_e32 v6, 1.0, v6
	v_rcp_f32_e32 v4, v4
	v_rcp_f32_e32 v5, v5
	v_rcp_f32_e32 v6, v6
	v_mul_f32_e32 v4, v153, v4
	v_mul_f32_e32 v5, v175, v5
	v_mul_f32_e32 v6, v203, v6
	v_fmac_f32_e32 v42, v137, v4
	v_fmac_f32_e32 v37, v137, v5
	v_fmac_f32_e32 v36, v137, v6
	v_mul_f32_e32 v4, 0xbfb8aa3b, v154
	v_mul_f32_e32 v5, 0xbfb8aa3b, v176
	v_mul_f32_e32 v6, 0xbfb8aa3b, v204
	v_exp_f32_e32 v4, v4
	v_exp_f32_e32 v5, v5
	v_exp_f32_e32 v6, v6
	v_add_f32_e32 v4, 1.0, v4
	v_add_f32_e32 v5, 1.0, v5
	v_add_f32_e32 v6, 1.0, v6
	v_rcp_f32_e32 v4, v4
	v_rcp_f32_e32 v5, v5
	v_rcp_f32_e32 v6, v6
	v_mul_f32_e32 v4, v154, v4
	v_mul_f32_e32 v5, v176, v5
	v_mul_f32_e32 v6, v204, v6
	v_fmac_f32_e32 v42, v138, v4
	v_fmac_f32_e32 v37, v138, v5
	v_fmac_f32_e32 v36, v138, v6
	v_mul_f32_e32 v4, 0xbfb8aa3b, v155
	v_mul_f32_e32 v5, 0xbfb8aa3b, v177
	v_mul_f32_e32 v6, 0xbfb8aa3b, v205
	v_exp_f32_e32 v4, v4
	v_exp_f32_e32 v5, v5
	v_exp_f32_e32 v6, v6
	v_add_f32_e32 v4, 1.0, v4
	v_add_f32_e32 v5, 1.0, v5
	v_add_f32_e32 v6, 1.0, v6
	v_rcp_f32_e32 v4, v4
	v_rcp_f32_e32 v5, v5
	v_rcp_f32_e32 v6, v6
	v_mul_f32_e32 v4, v155, v4
	v_mul_f32_e32 v5, v177, v5
	v_mul_f32_e32 v6, v205, v6
	v_fmac_f32_e32 v42, v139, v4
	v_fmac_f32_e32 v37, v139, v5
	v_fmac_f32_e32 v36, v139, v6
	v_mul_f32_e32 v4, 0xbfb8aa3b, v156
	v_mul_f32_e32 v5, 0xbfb8aa3b, v178
	v_mul_f32_e32 v6, 0xbfb8aa3b, v206
	v_exp_f32_e32 v4, v4
	v_exp_f32_e32 v5, v5
	v_exp_f32_e32 v6, v6
	v_add_f32_e32 v4, 1.0, v4
	v_add_f32_e32 v5, 1.0, v5
	v_add_f32_e32 v6, 1.0, v6
	v_rcp_f32_e32 v4, v4
	v_rcp_f32_e32 v5, v5
	v_rcp_f32_e32 v6, v6
	v_mul_f32_e32 v4, v156, v4
	v_mul_f32_e32 v5, v178, v5
	v_mul_f32_e32 v6, v206, v6
	v_fmac_f32_e32 v42, v140, v4
	v_fmac_f32_e32 v37, v140, v5
	v_fmac_f32_e32 v36, v140, v6
	v_mul_f32_e32 v4, 0xbfb8aa3b, v157
	v_mul_f32_e32 v5, 0xbfb8aa3b, v179
	v_mul_f32_e32 v6, 0xbfb8aa3b, v207
	v_exp_f32_e32 v4, v4
	v_exp_f32_e32 v5, v5
	v_exp_f32_e32 v6, v6
	v_add_f32_e32 v4, 1.0, v4
	v_add_f32_e32 v5, 1.0, v5
	v_add_f32_e32 v6, 1.0, v6
	v_rcp_f32_e32 v4, v4
	v_rcp_f32_e32 v5, v5
	v_rcp_f32_e32 v6, v6
	v_mul_f32_e32 v4, v157, v4
	v_mul_f32_e32 v5, v179, v5
	v_mul_f32_e32 v6, v207, v6
	v_fmac_f32_e32 v42, v141, v4
	v_fmac_f32_e32 v37, v141, v5
	v_fmac_f32_e32 v36, v141, v6
	v_mul_f32_e32 v4, 0xbfb8aa3b, v158
	v_mul_f32_e32 v5, 0xbfb8aa3b, v180
	v_mul_f32_e32 v6, 0xbfb8aa3b, v208
	v_exp_f32_e32 v4, v4
	v_exp_f32_e32 v5, v5
	v_exp_f32_e32 v6, v6
	v_add_f32_e32 v4, 1.0, v4
	v_add_f32_e32 v5, 1.0, v5
	v_add_f32_e32 v6, 1.0, v6
	v_rcp_f32_e32 v4, v4
	v_rcp_f32_e32 v5, v5
	v_rcp_f32_e32 v6, v6
	v_mul_f32_e32 v4, v158, v4
	v_mul_f32_e32 v5, v180, v5
	v_mul_f32_e32 v6, v208, v6
	v_fmac_f32_e32 v42, v142, v4
	v_fmac_f32_e32 v37, v142, v5
	v_fmac_f32_e32 v36, v142, v6
	v_mul_f32_e32 v4, 0xbfb8aa3b, v159
	v_mul_f32_e32 v5, 0xbfb8aa3b, v181
	v_mul_f32_e32 v6, 0xbfb8aa3b, v209
	v_exp_f32_e32 v4, v4
	v_exp_f32_e32 v5, v5
	v_exp_f32_e32 v6, v6
	v_add_f32_e32 v4, 1.0, v4
	v_add_f32_e32 v5, 1.0, v5
	v_add_f32_e32 v6, 1.0, v6
	v_rcp_f32_e32 v4, v4
	v_rcp_f32_e32 v5, v5
	v_rcp_f32_e32 v6, v6
	v_mul_f32_e32 v4, v159, v4
	v_mul_f32_e32 v5, v181, v5
	v_mul_f32_e32 v6, v209, v6
	v_fmac_f32_e32 v42, v143, v4
	v_fmac_f32_e32 v37, v143, v5
	v_fmac_f32_e32 v36, v143, v6
	v_mul_f32_e32 v4, 0xbfb8aa3b, v160
	v_mul_f32_e32 v5, 0xbfb8aa3b, v182
	v_mul_f32_e32 v6, 0xbfb8aa3b, v210
	v_exp_f32_e32 v4, v4
	v_exp_f32_e32 v5, v5
	v_exp_f32_e32 v6, v6
	v_add_f32_e32 v4, 1.0, v4
	v_add_f32_e32 v5, 1.0, v5
	v_add_f32_e32 v6, 1.0, v6
; __device__ __forceinline__ float silu_f(float x) { return x * __builtin_amdgcn_rcpf(1.f + __builtin_amdgcn_exp2f(-x * 1.4426950408889634f)); }
; __device__ __forceinline__ void p0_prologue(const LArgs& a, LAS unsigned char* lds) {
;     ...
;             for (int k = 0; k < 256; ++k) { const float wv = w[(size_t)k * 12288]; a0 += pg8::silu_f(c0[k]) * wv; a1 += pg8::silu_f(c1[k]) * wv; a2 += pg8::silu_f(c2[k]) * wv; }
;             if (kc == 0) { const float bb = a.in(I_ADAB)[layer * 12288 + col]; a0 += bb; a1 += bb; a2 += bb; }
;             float* m = mods + (size_t)layer * 3 * 12288 + col;
;             atomicAdd(m, a0); atomicAdd(m + 12288, a1); atomicAdd(m + 2 * 12288, a2);
	v_rcp_f32_e32 v4, v4
	v_rcp_f32_e32 v5, v5
	v_rcp_f32_e32 v6, v6
	v_mul_f32_e32 v4, v160, v4
	v_mul_f32_e32 v5, v182, v5
	v_mul_f32_e32 v6, v210, v6
	v_fmac_f32_e32 v42, v144, v4
	v_fmac_f32_e32 v37, v144, v5
	v_fmac_f32_e32 v36, v144, v6
	v_mul_f32_e32 v4, 0xbfb8aa3b, v161
	v_mul_f32_e32 v5, 0xbfb8aa3b, v183
	v_mul_f32_e32 v6, 0xbfb8aa3b, v211
	v_exp_f32_e32 v4, v4
	v_exp_f32_e32 v5, v5
	v_exp_f32_e32 v6, v6
	v_add_f32_e32 v4, 1.0, v4
	v_add_f32_e32 v5, 1.0, v5
	v_add_f32_e32 v6, 1.0, v6
	v_rcp_f32_e32 v4, v4
	v_rcp_f32_e32 v5, v5
	v_rcp_f32_e32 v6, v6
	v_mul_f32_e32 v4, v161, v4
	v_mul_f32_e32 v5, v183, v5
	v_mul_f32_e32 v6, v211, v6
	v_fmac_f32_e32 v42, v145, v4
	v_fmac_f32_e32 v37, v145, v5
	v_fmac_f32_e32 v36, v145, v6
	v_mul_f32_e32 v4, 0xbfb8aa3b, v162
	v_mul_f32_e32 v5, 0xbfb8aa3b, v184
	v_mul_f32_e32 v6, 0xbfb8aa3b, v212
	v_exp_f32_e32 v4, v4
	v_exp_f32_e32 v5, v5
	v_exp_f32_e32 v6, v6
	v_add_f32_e32 v4, 1.0, v4
	v_add_f32_e32 v5, 1.0, v5
	v_add_f32_e32 v6, 1.0, v6
	v_rcp_f32_e32 v4, v4
	v_rcp_f32_e32 v5, v5
	v_rcp_f32_e32 v6, v6
	v_mul_f32_e32 v4, v162, v4
	v_mul_f32_e32 v5, v184, v5
	v_mul_f32_e32 v6, v212, v6
	v_fmac_f32_e32 v42, v146, v4
	v_fmac_f32_e32 v37, v146, v5
	v_fmac_f32_e32 v36, v146, v6
	v_mul_f32_e32 v4, 0xbfb8aa3b, v163
	v_mul_f32_e32 v5, 0xbfb8aa3b, v185
	v_mul_f32_e32 v6, 0xbfb8aa3b, v213
	v_exp_f32_e32 v4, v4
	v_exp_f32_e32 v5, v5
	v_exp_f32_e32 v6, v6
	v_add_f32_e32 v4, 1.0, v4
	v_add_f32_e32 v5, 1.0, v5
	v_add_f32_e32 v6, 1.0, v6
	v_rcp_f32_e32 v4, v4
	v_rcp_f32_e32 v5, v5
	v_rcp_f32_e32 v6, v6
	v_mul_f32_e32 v4, v163, v4
	v_mul_f32_e32 v5, v185, v5
	v_mul_f32_e32 v6, v213, v6
	v_fmac_f32_e32 v42, v147, v4
	v_fmac_f32_e32 v37, v147, v5
	v_fmac_f32_e32 v36, v147, v6
	v_mul_f32_e32 v4, 0xbfb8aa3b, v164
	v_mul_f32_e32 v5, 0xbfb8aa3b, v186
	v_mul_f32_e32 v6, 0xbfb8aa3b, v214
	v_exp_f32_e32 v4, v4
	v_exp_f32_e32 v5, v5
	v_exp_f32_e32 v6, v6
	v_add_f32_e32 v4, 1.0, v4
	v_add_f32_e32 v5, 1.0, v5
	v_add_f32_e32 v6, 1.0, v6
	v_rcp_f32_e32 v4, v4
	v_rcp_f32_e32 v5, v5
	v_rcp_f32_e32 v6, v6
	v_mul_f32_e32 v4, v164, v4
	v_mul_f32_e32 v5, v186, v5
	v_mul_f32_e32 v6, v214, v6
	v_fmac_f32_e32 v42, v148, v4
	v_fmac_f32_e32 v37, v148, v5
	v_fmac_f32_e32 v36, v148, v6
	v_mul_f32_e32 v4, 0xbfb8aa3b, v165
	v_mul_f32_e32 v5, 0xbfb8aa3b, v187
	v_mul_f32_e32 v6, 0xbfb8aa3b, v215
	v_exp_f32_e32 v4, v4
	v_exp_f32_e32 v5, v5
	v_exp_f32_e32 v6, v6
	v_add_f32_e32 v4, 1.0, v4
	v_add_f32_e32 v5, 1.0, v5
	v_add_f32_e32 v6, 1.0, v6
	v_rcp_f32_e32 v4, v4
	v_rcp_f32_e32 v5, v5
	v_rcp_f32_e32 v6, v6
	v_mul_f32_e32 v4, v165, v4
	v_mul_f32_e32 v5, v187, v5
	v_mul_f32_e32 v6, v215, v6
	v_fmac_f32_e32 v42, v149, v4
	v_fmac_f32_e32 v37, v149, v5
	v_fmac_f32_e32 v36, v149, v6
	v_mul_f32_e32 v4, 0xbfb8aa3b, v166
	v_mul_f32_e32 v5, 0xbfb8aa3b, v188
	v_mul_f32_e32 v6, 0xbfb8aa3b, v216
	v_exp_f32_e32 v4, v4
	v_exp_f32_e32 v5, v5
	v_exp_f32_e32 v6, v6
	v_add_f32_e32 v4, 1.0, v4
	v_add_f32_e32 v5, 1.0, v5
	v_add_f32_e32 v6, 1.0, v6
	v_rcp_f32_e32 v4, v4
	v_rcp_f32_e32 v5, v5
	v_rcp_f32_e32 v6, v6
	v_mul_f32_e32 v4, v166, v4
	v_mul_f32_e32 v5, v188, v5
	v_mul_f32_e32 v6, v216, v6
	v_fmac_f32_e32 v42, v150, v4
	v_fmac_f32_e32 v37, v150, v5
	v_fmac_f32_e32 v36, v150, v6
	v_mul_f32_e32 v4, 0xbfb8aa3b, v167
	v_mul_f32_e32 v5, 0xbfb8aa3b, v189
	v_mul_f32_e32 v6, 0xbfb8aa3b, v217
	v_exp_f32_e32 v4, v4
	v_exp_f32_e32 v5, v5
	v_exp_f32_e32 v6, v6
	v_add_f32_e32 v4, 1.0, v4
	v_add_f32_e32 v5, 1.0, v5
	v_add_f32_e32 v6, 1.0, v6
	v_rcp_f32_e32 v4, v4
	v_rcp_f32_e32 v5, v5
	v_rcp_f32_e32 v6, v6
	v_mul_f32_e32 v4, v167, v4
	v_mul_f32_e32 v5, v189, v5
	v_mul_f32_e32 v6, v217, v6
	v_fmac_f32_e32 v42, v151, v4
	v_fmac_f32_e32 v37, v151, v5
	v_fmac_f32_e32 v36, v151, v6
	v_cmp_eq_u32_e32 vcc, 0, v43
	s_and_saveexec_b64 s[6:7], vcc
	s_cbranch_execz .LBB0_471
	v_mov_b32_e32 v4, s65
	ds_read_b64 v[4:5], v4 offset:40
	v_mad_i32_i24 v6, v41, s10, v28
	v_ashrrev_i32_e32 v7, 31, v6
	s_waitcnt lgkmcnt(0)
	v_readfirstlane_b32 s2, v5
	v_readfirstlane_b32 s3, v4
	s_nop 0
	v_mov_b32_e32 v5, s2
	v_mov_b32_e32 v4, s3
	v_lshl_add_u64 v[4:5], v[6:7], 2, v[4:5]
	global_load_dword v4, v[4:5], off
	s_waitcnt vmcnt(0)
	v_add_f32_e32 v42, v42, v4
	v_pk_add_f32 v[36:37], v[36:37], v[4:5] op_sel_hi:[1,0]
	s_branch .LBB0_471
